# attention rescale: packed v_pk_mul_f32 on the O accumulators split into scalar v_mul_f32 pairs (instruction selection, bit-identical)
# speedup vs baseline: 1.0023x; 1.0023x over previous
; __device__ __forceinline__ void attn_item(const int tid, char* smem, const Params& p, int l, int item) {
;     ...
;     f32x4 S[2][4];
; #pragma unroll
;     for (int h = 0; h < 2; ++h)
; #pragma unroll
;       for (int kb = 0; kb < 4; ++kb) {
;         f32x4 s = (f32x4){0.f, 0.f, 0.f, 0.f};
; #pragma unroll
;         for (int ks = 0; ks < 2; ++ks) {
;           bf16x8 kf = *reinterpret_cast<const bf16x8*>(Ks + (kb * 16 + fr) * 288 + (h * 64 + ks * 32 + fq * 8) * 2);
;           s = __builtin_amdgcn_mfma_f32_16x16x32_bf16(kf, qf[h][ks], s, 0, 0, 0);
;         }
;         S[h][kb] = s;
;       }
;     bf16x8 pf[2][2];
; #pragma unroll
;     for (int h = 0; h < 2; ++h) {
;       float mx = -INFINITY;
; #pragma unroll
;       for (int kb = 0; kb < 4; ++kb)
; #pragma unroll
;         for (int r = 0; r < 4; ++r) mx = fmaxf(mx, S[h][kb][r]);
;       mx = fmaxf(mx, __shfl_xor(mx, 16));
;       mx = fmaxf(mx, __shfl_xor(mx, 32));
;       const float mold = mrun[h];
;       const float mnew = fmaxf(mold, mx);
;       mrun[h] = mnew;
;       float ps = 0.f;
;       float pv[4][4];
; #pragma unroll
;       for (int kb = 0; kb < 4; ++kb)
; #pragma unroll
;         for (int r = 0; r < 4; ++r) {
;           pv[kb][r] = __builtin_amdgcn_exp2f(S[h][kb][r] - mnew);
;           ps += pv[kb][r];
;         }
;       if (__builtin_amdgcn_ballot_w64(mnew > mold) != 0ull) {
;         const float alpha = __builtin_amdgcn_exp2f(mold - mnew);
;         lrun[h] *= alpha;
; #pragma unroll
;         for (int vb = 0; vb < 8; ++vb) O[h][vb] *= alpha;
;       }
;       lrun[h] += ps;
.LBB0_100:
	s_bitcmp1_b32 s1, 0
	s_cselect_b32 s1, 0xd800, 0
	v_add_u32_e32 v16, s1, v211
	ds_read_b128 v[128:131], v16
	ds_read_b128 v[120:123], v16 offset:64
	ds_read_b128 v[124:127], v16 offset:4608
	ds_read_b128 v[116:119], v16 offset:4672
	ds_read_b128 v[104:107], v16 offset:9216
	ds_read_b128 v[112:115], v16 offset:9280
	ds_read_b128 v[100:103], v16 offset:13824
	ds_read_b128 v[108:111], v16 offset:13888
	s_waitcnt lgkmcnt(6)
	v_mfma_f32_16x16x32_bf16 v[128:131], v[128:131], v[0:3], 0
	v_mfma_f32_16x16x32_bf16 v[128:131], v[120:123], v[4:7], v[128:131]
	ds_read_b128 v[120:123], v16 offset:128
	ds_read_b128 v[218:221], v16 offset:192
	s_waitcnt lgkmcnt(6)
	v_mfma_f32_16x16x32_bf16 v[124:127], v[124:127], v[0:3], 0
	v_mfma_f32_16x16x32_bf16 v[124:127], v[116:119], v[4:7], v[124:127]
	ds_read_b128 v[116:119], v16 offset:4736
	ds_read_b128 v[148:151], v16 offset:4800
	s_waitcnt lgkmcnt(6)
	v_mfma_f32_16x16x32_bf16 v[104:107], v[104:107], v[0:3], 0
	v_mfma_f32_16x16x32_bf16 v[104:107], v[112:115], v[4:7], v[104:107]
	ds_read_b128 v[112:115], v16 offset:9344
	s_waitcnt lgkmcnt(5)
	v_mfma_f32_16x16x32_bf16 v[100:103], v[100:103], v[0:3], 0
	v_mfma_f32_16x16x32_bf16 v[100:103], v[108:111], v[4:7], v[100:103]
	ds_read_b128 v[108:111], v16 offset:13952
	s_waitcnt lgkmcnt(4)
	v_mfma_f32_16x16x32_bf16 v[120:123], v[120:123], v[8:11], 0
	v_mfma_f32_16x16x32_bf16 v[120:123], v[218:221], v[12:15], v[120:123]
	ds_read_b128 v[218:221], v16 offset:9408
	v_max3_f32 v17, v128, s28, v129
	v_max3_f32 v17, v17, v130, v131
	v_max3_f32 v17, v17, v124, v125
	v_max3_f32 v17, v17, v126, v127
	v_max3_f32 v17, v17, v104, v105
	v_max3_f32 v17, v17, v106, v107
	s_waitcnt lgkmcnt(3)
	v_mfma_f32_16x16x32_bf16 v[116:119], v[116:119], v[8:11], 0
	v_mfma_f32_16x16x32_bf16 v[116:119], v[148:151], v[12:15], v[116:119]
	ds_read_b128 v[148:151], v16 offset:14016
	v_max3_f32 v17, v17, v100, v101
	v_max3_f32 v17, v17, v102, v103
	ds_bpermute_b32 v19, v172, v17
	s_waitcnt lgkmcnt(2)
	v_mfma_f32_16x16x32_bf16 v[112:115], v[112:115], v[8:11], 0
	v_mfma_f32_16x16x32_bf16 v[112:115], v[218:221], v[12:15], v[112:115]
	s_waitcnt lgkmcnt(1)
	v_mfma_f32_16x16x32_bf16 v[108:111], v[108:111], v[8:11], 0
	v_mfma_f32_16x16x32_bf16 v[108:111], v[148:151], v[12:15], v[108:111]
	s_waitcnt lgkmcnt(0)
	v_max_f32_e32 v19, v19, v19
	v_max_f32_e32 v17, v17, v19
	ds_bpermute_b32 v19, v153, v17
	s_waitcnt lgkmcnt(0)
	v_max3_f32 v17, v216, v17, v19
	v_cmp_gt_f32_e32 vcc, v17, v216
	s_cbranch_vccz .LBB0_102
	v_sub_f32_e32 v19, v216, v17
	v_exp_f32_e32 v148, v19
	s_nop 0
	v_mul_f32_e32 v155, v155, v148
	v_mul_f32_e32 v86, v148, v86
	v_mul_f32_e32 v87, v148, v87
	v_mul_f32_e32 v84, v148, v84
	v_mul_f32_e32 v85, v148, v85
	v_mul_f32_e32 v74, v148, v74
	v_mul_f32_e32 v75, v148, v75
	v_mul_f32_e32 v72, v148, v72
	v_mul_f32_e32 v73, v148, v73
	v_mul_f32_e32 v62, v148, v62
	v_mul_f32_e32 v63, v148, v63
	v_mul_f32_e32 v60, v148, v60
	v_mul_f32_e32 v61, v148, v61
	v_mul_f32_e32 v50, v148, v50
	v_mul_f32_e32 v51, v148, v51
	v_mul_f32_e32 v48, v148, v48
	v_mul_f32_e32 v49, v148, v49
	v_mul_f32_e32 v38, v148, v38
	v_mul_f32_e32 v39, v148, v39
	v_mul_f32_e32 v36, v148, v36
	v_mul_f32_e32 v37, v148, v37
	v_mul_f32_e32 v58, v148, v58
	v_mul_f32_e32 v59, v148, v59
	v_mul_f32_e32 v56, v148, v56
	v_mul_f32_e32 v57, v148, v57
	v_mul_f32_e32 v42, v148, v42
	v_mul_f32_e32 v43, v148, v43
	v_mul_f32_e32 v40, v148, v40
	v_mul_f32_e32 v41, v148, v41
	v_mul_f32_e32 v94, v148, v94
	v_mul_f32_e32 v95, v148, v95
	v_mul_f32_e32 v92, v148, v92
	v_mul_f32_e32 v93, v148, v93
.LBB0_102:
	v_max3_f32 v19, v120, s28, v121
	v_max3_f32 v19, v19, v122, v123
	v_max3_f32 v19, v19, v116, v117
	v_max3_f32 v19, v19, v118, v119
	v_max3_f32 v19, v19, v112, v113
	v_max3_f32 v19, v19, v114, v115
	s_nop 0
	v_max3_f32 v19, v19, v108, v109
	v_max3_f32 v19, v19, v110, v111
	ds_bpermute_b32 v148, v172, v19
	s_waitcnt lgkmcnt(0)
	v_max_f32_e32 v148, v148, v148
	v_max_f32_e32 v19, v19, v148
	ds_bpermute_b32 v148, v153, v19
	s_waitcnt lgkmcnt(0)
	v_max3_f32 v19, v217, v19, v148
	v_cmp_gt_f32_e32 vcc, v19, v217
	s_cbranch_vccz .LBB0_104
	v_sub_f32_e32 v148, v217, v19
	v_exp_f32_e32 v148, v148
	s_nop 0
	v_mul_f32_e32 v215, v215, v148
	v_mul_f32_e32 v90, v148, v90
	v_mul_f32_e32 v91, v148, v91
	v_mul_f32_e32 v88, v148, v88
	v_mul_f32_e32 v89, v148, v89
	v_mul_f32_e32 v82, v148, v82
	v_mul_f32_e32 v83, v148, v83
	v_mul_f32_e32 v80, v148, v80
	v_mul_f32_e32 v81, v148, v81
	v_mul_f32_e32 v78, v148, v78
	v_mul_f32_e32 v79, v148, v79
	v_mul_f32_e32 v76, v148, v76
	v_mul_f32_e32 v77, v148, v77
	v_mul_f32_e32 v66, v148, v66
	v_mul_f32_e32 v67, v148, v67
	v_mul_f32_e32 v64, v148, v64
	v_mul_f32_e32 v65, v148, v65
	v_mul_f32_e32 v46, v148, v46
	v_mul_f32_e32 v47, v148, v47
	v_mul_f32_e32 v44, v148, v44
	v_mul_f32_e32 v45, v148, v45
	v_mul_f32_e32 v70, v148, v70
	v_mul_f32_e32 v71, v148, v71
	v_mul_f32_e32 v68, v148, v68
	v_mul_f32_e32 v69, v148, v69
	v_mul_f32_e32 v54, v148, v54
	v_mul_f32_e32 v55, v148, v55
	v_mul_f32_e32 v52, v148, v52
	v_mul_f32_e32 v53, v148, v53
	v_mul_f32_e32 v98, v148, v98
	v_mul_f32_e32 v99, v148, v99
	v_mul_f32_e32 v96, v148, v96
	v_mul_f32_e32 v97, v148, v97
